# attention inter-barrier segments: 8 already-satisfied vmcnt waits and one dead v_add removed (issue slots on the barrier-to-barrier path)
# baseline (speedup 1.0000x reference)
.LBB0_561:
	ds_read_b128 v[64:67], v189 offset:49152
	ds_read_b128 v[68:71], v189 offset:57344
	ds_read_b128 v[210:213], v190 offset:49152
	ds_read_b128 v[218:221], v190 offset:57344
	s_add_i32 s0, 0, 0x12000
	s_waitcnt lgkmcnt(3)
	v_mfma_f32_32x32x16_bf16 v[80:95], v[64:67], v[120:123], 0
	v_xor_b32_e32 v241, v243, v158
	s_add_u32 s100, s64, 0x34e80000
	s_addc_u32 s101, s65, 0
	s_lshl_b32 m0, s33, 4
	s_add_i32 m0, m0, 0x8000
	s_nop 0
	global_load_lds_dwordx4 v241, s[100:101]
	s_add_u32 s100, s64, 0x34ea0000
	s_addc_u32 s101, s65, 0
	s_add_i32 m0, m0, 0x2000
	s_nop 0
	global_load_lds_dwordx4 v241, s[100:101]
	v_xor_b32_e32 v241, v242, v170
	s_add_u32 s100, s64, 0x1ea04000
	s_addc_u32 s101, s65, 0
	s_add_i32 m0, m0, 0x6000
	s_nop 0
	global_load_lds_dwordx4 v241, s[100:101]
	v_exp_f32_e32 v175, v175
	v_exp_f32_e32 v217, v217
	v_add_f32_e32 v148, 0, v175
	s_waitcnt lgkmcnt(2)
	v_mfma_f32_32x32x16_bf16 v[64:79], v[68:71], v[120:123], 0
	v_exp_f32_e32 v149, v149
	v_add_f32_e32 v148, v217, v148
	v_exp_f32_e32 v216, v216
	s_waitcnt lgkmcnt(1)
	v_mfma_f32_32x32x16_bf16 v[80:95], v[210:213], v[124:127], v[80:95]
	v_add_f32_e32 v148, v149, v148
	v_exp_f32_e32 v150, v150
	v_add_f32_e32 v148, v216, v148
	s_waitcnt lgkmcnt(0)
	v_mfma_f32_32x32x16_bf16 v[64:79], v[218:221], v[124:127], v[64:79]
	ds_read_b128 v[210:213], v191 offset:49152
	ds_read_b128 v[218:221], v191 offset:57344
	v_exp_f32_e32 v174, v174
	v_add_f32_e32 v148, v150, v148
	v_exp_f32_e32 v151, v151
	v_add_f32_e32 v148, v174, v148
	s_waitcnt lgkmcnt(1)
	v_mfma_f32_32x32x16_bf16 v[80:95], v[210:213], v[116:119], v[80:95]
	v_exp_f32_e32 v173, v173
	v_add_f32_e32 v148, v151, v148
	v_exp_f32_e32 v154, v154
	s_waitcnt lgkmcnt(0)
	v_mfma_f32_32x32x16_bf16 v[64:79], v[218:221], v[116:119], v[64:79]
	ds_read_b128 v[210:213], v192 offset:49152
	ds_read_b128 v[218:221], v192 offset:57344
	v_add_f32_e32 v148, v173, v148
	v_exp_f32_e32 v172, v172
	v_add_f32_e32 v148, v154, v148
	s_waitcnt lgkmcnt(1)
	v_mfma_f32_32x32x16_bf16 v[80:95], v[210:213], v[112:115], v[80:95]
	v_exp_f32_e32 v153, v153
	v_add_f32_e32 v148, v172, v148
	v_exp_f32_e32 v155, v155
	v_add_f32_e32 v148, v153, v148
	s_waitcnt lgkmcnt(0)
	v_mfma_f32_32x32x16_bf16 v[64:79], v[218:221], v[112:115], v[64:79]
	ds_read_b128 v[210:213], v193 offset:49152
	ds_read_b128 v[218:221], v193 offset:57344
	ds_read_b128 v[232:235], v194 offset:49152
	ds_read_b128 v[236:239], v194 offset:57344
	v_exp_f32_e32 v145, v145
	v_add_f32_e32 v148, v155, v148
	v_exp_f32_e32 v140, v140
	s_waitcnt lgkmcnt(3)
	v_mfma_f32_32x32x16_bf16 v[80:95], v[210:213], v[108:111], v[80:95]
	v_exp_f32_e32 v147, v147
	v_add_f32_e32 v148, v145, v148
	v_exp_f32_e32 v141, v141
	s_waitcnt lgkmcnt(2)
	v_mfma_f32_32x32x16_bf16 v[64:79], v[218:221], v[108:111], v[64:79]
	ds_read_b128 v[210:213], v195 offset:49152
	ds_read_b128 v[218:221], v195 offset:57344
	v_exp_f32_e32 v144, v144
	v_add_f32_e32 v148, v147, v148
	v_exp_f32_e32 v138, v138
	v_exp_f32_e32 v146, v146
	s_waitcnt lgkmcnt(3)
	v_mfma_f32_32x32x16_bf16 v[80:95], v[232:235], v[104:107], v[80:95]
	v_add_f32_e32 v148, v144, v148
	v_exp_f32_e32 v139, v139
	v_add_f32_e32 v148, v146, v148
	s_waitcnt lgkmcnt(2)
	v_mfma_f32_32x32x16_bf16 v[64:79], v[236:239], v[104:107], v[64:79]
	ds_read_b128 v[232:235], v196 offset:49152
	ds_read_b128 v[236:239], v196 offset:57344
	v_exp_f32_e32 v132, v132
	v_add_f32_e32 v148, v140, v148
	v_exp_f32_e32 v133, v133
	s_waitcnt lgkmcnt(3)
	v_mfma_f32_32x32x16_bf16 v[80:95], v[210:213], v[100:103], v[80:95]
	v_add_u32_e32 v230, s0, v198
	v_add_u32_e32 v231, s0, v200
	v_add_f32_e32 v148, v141, v148
	v_exp_f32_e32 v130, v130
	v_add_f32_e32 v148, v138, v148
	v_exp_f32_e32 v131, v131
	s_waitcnt lgkmcnt(2)
	v_mfma_f32_32x32x16_bf16 v[64:79], v[218:221], v[100:103], v[64:79]
	ds_read_b128 v[210:213], v230
	ds_read_b128 v[218:221], v230 offset:4096
	ds_read_b128 v[222:225], v197
	v_add_f32_e32 v148, v139, v148
	v_exp_f32_e32 v128, v128
	v_add_f32_e32 v148, v132, v148
	s_waitcnt lgkmcnt(4)
	v_mfma_f32_32x32x16_bf16 v[80:95], v[232:235], v[96:99], v[80:95]
	v_exp_f32_e32 v129, v129
	v_add_f32_e32 v148, v133, v148
	v_exp_f32_e32 v142, v142
	s_waitcnt lgkmcnt(3)
	v_mfma_f32_32x32x16_bf16 v[64:79], v[236:239], v[96:99], v[64:79]
	ds_read_b128 v[232:235], v231
	ds_read_b128 v[236:239], v231 offset:4096
	ds_read_b128 v[226:229], v184
	v_add_f32_e32 v148, v130, v148
	v_exp_f32_e32 v143, v143
	v_add_f32_e32 v148, v131, v148
	v_exp_f32_e32 v136, v136
	s_waitcnt lgkmcnt(3)
	v_mfma_f32_32x32x16_bf16 v[80:95], v[210:213], v[222:225], v[80:95]
	v_add_f32_e32 v148, v128, v148
	v_exp_f32_e32 v137, v137
	v_add_f32_e32 v148, v129, v148
	v_mfma_f32_32x32x16_bf16 v[64:79], v[218:221], v[222:225], v[64:79]
	v_add_u32_e32 v244, s0, v202
	v_add_u32_e32 v247, s0, v204
	ds_read_b128 v[210:213], v244
	ds_read_b128 v[218:221], v244 offset:4096
	ds_read_b128 v[222:225], v183
	v_exp_f32_e32 v134, v134
	v_add_f32_e32 v148, v142, v148
	v_exp_f32_e32 v135, v135
	s_waitcnt lgkmcnt(3)
	v_mfma_f32_32x32x16_bf16 v[80:95], v[232:235], v[226:229], v[80:95]
	v_add_f32_e32 v148, v143, v148
	v_add_f32_e32 v148, v136, v148
	v_add_f32_e32 v148, v137, v148
	v_add_f32_e32 v148, v134, v148
	v_add_f32_e32 v214, v135, v148
	v_mov_b32_e32 v215, v214
	s_nop 1
	v_permlane32_swap_b32_e32 v214, v215
	v_mfma_f32_32x32x16_bf16 v[64:79], v[236:239], v[226:229], v[64:79]
	ds_read_b128 v[232:235], v247
	ds_read_b128 v[236:239], v247 offset:4096
	ds_read_b128 v[226:229], v182
	s_waitcnt lgkmcnt(3)
	v_mfma_f32_32x32x16_bf16 v[80:95], v[210:213], v[222:225], v[80:95]
	v_mfma_f32_32x32x16_bf16 v[64:79], v[218:221], v[222:225], v[64:79]
	v_cvt_pk_bf16_f32 v148, v175, v217
	v_cvt_pk_bf16_f32 v149, v149, v216
	v_cvt_pk_bf16_f32 v150, v150, v174
	v_cvt_pk_bf16_f32 v151, v151, v173
	v_cvt_pk_bf16_f32 v152, v154, v172
	v_cvt_pk_bf16_f32 v153, v153, v155
	s_waitcnt lgkmcnt(0)
	v_mfma_f32_32x32x16_bf16 v[80:95], v[232:235], v[226:229], v[80:95]
	v_cvt_pk_bf16_f32 v154, v145, v147
	v_permlane32_swap_b32_e32 v148, v150
	v_cvt_pk_bf16_f32 v155, v144, v146
	v_permlane32_swap_b32_e32 v152, v154
	v_cvt_pk_bf16_f32 v216, v140, v141
	v_mfma_f32_32x32x16_bf16 v[64:79], v[236:239], v[226:229], v[64:79]
	ds_read_b64_tr_b16 v[224:225], v181 offset:0
	ds_read_b64_tr_b16 v[226:227], v181 offset:0x800
	ds_read_b64_tr_b16 v[228:229], v181 offset:0x1000
	ds_read_b64_tr_b16 v[230:231], v181 offset:0x1800
	ds_read_b64_tr_b16 v[232:233], v181 offset:0x2000
	ds_read_b64_tr_b16 v[234:235], v181 offset:0x2800
	ds_read_b64_tr_b16 v[236:237], v181 offset:0x3000
	ds_read_b64_tr_b16 v[238:239], v181 offset:0x3800
	v_cvt_pk_bf16_f32 v217, v138, v139
	v_cvt_pk_bf16_f32 v218, v132, v133
	v_cvt_pk_bf16_f32 v219, v130, v131
	v_cvt_pk_bf16_f32 v220, v128, v129
	v_cvt_pk_bf16_f32 v221, v142, v143
	v_cvt_pk_bf16_f32 v222, v136, v137
	v_cvt_pk_bf16_f32 v223, v134, v135
	v_permlane32_swap_b32_e32 v149, v151
	v_permlane32_swap_b32_e32 v153, v155
	v_permlane32_swap_b32_e32 v216, v218
	v_permlane32_swap_b32_e32 v217, v219
	v_permlane32_swap_b32_e32 v220, v222
	v_permlane32_swap_b32_e32 v221, v223
	v_lshl_add_u64 v[172:173], s[64:65], 0, v[158:159]
	s_mov_b32 s0, 0x34e80000
	v_add_co_u32_e32 v132, vcc, s0, v172
	s_mov_b32 s0, 0x34ea0000
	s_nop 0
	v_addc_co_u32_e32 v133, vcc, 0, v173, vcc
	v_add_co_u32_e32 v136, vcc, s0, v172
	v_lshl_add_u64 v[174:175], s[64:65], 0, v[170:171]
	s_nop 0
	v_addc_co_u32_e32 v137, vcc, 0, v173, vcc
	global_load_dwordx4 v[128:131], v[132:133], off offset:256
	s_nop 0
	s_nop 0
	global_load_dwordx4 v[140:143], v[136:137], off offset:256
	s_nop 0
	s_mov_b32 s0, 0x1ea04000
	s_nop 0
	s_waitcnt lgkmcnt(6)
	v_mfma_f32_32x32x16_bf16 v[0:15], v[148:151], v[224:227], v[0:15]
	ds_read_b64_tr_b16 v[224:225], v181 offset:0x200
	ds_read_b64_tr_b16 v[226:227], v181 offset:0xa00
	s_waitcnt lgkmcnt(6)
	v_mfma_f32_32x32x16_bf16 v[0:15], v[152:155], v[228:231], v[0:15]
	ds_read_b64_tr_b16 v[228:229], v181 offset:0x1200
	ds_read_b64_tr_b16 v[230:231], v181 offset:0x1a00
	s_waitcnt lgkmcnt(6)
	v_mfma_f32_32x32x16_bf16 v[0:15], v[216:219], v[232:235], v[0:15]
	ds_read_b64_tr_b16 v[232:233], v181 offset:0x2200
	ds_read_b64_tr_b16 v[234:235], v181 offset:0x2a00
	s_waitcnt lgkmcnt(6)
	v_mfma_f32_32x32x16_bf16 v[0:15], v[220:223], v[236:239], v[0:15]
	ds_read_b64_tr_b16 v[236:237], v181 offset:0x3200
	ds_read_b64_tr_b16 v[238:239], v181 offset:0x3a00
	s_waitcnt lgkmcnt(6)
	v_mfma_f32_32x32x16_bf16 v[48:63], v[148:151], v[224:227], v[48:63]
	ds_read_b64_tr_b16 v[224:225], v181 offset:0x400
	ds_read_b64_tr_b16 v[226:227], v181 offset:0xc00
	s_waitcnt lgkmcnt(6)
	v_mfma_f32_32x32x16_bf16 v[48:63], v[152:155], v[228:231], v[48:63]
	ds_read_b64_tr_b16 v[228:229], v181 offset:0x1400
	ds_read_b64_tr_b16 v[230:231], v181 offset:0x1c00
	s_waitcnt lgkmcnt(6)
	v_mfma_f32_32x32x16_bf16 v[48:63], v[216:219], v[232:235], v[48:63]
	ds_read_b64_tr_b16 v[232:233], v181 offset:0x2400
	ds_read_b64_tr_b16 v[234:235], v181 offset:0x2c00
	s_waitcnt lgkmcnt(6)
	v_mfma_f32_32x32x16_bf16 v[48:63], v[220:223], v[236:239], v[48:63]
	ds_read_b64_tr_b16 v[236:237], v181 offset:0x3400
	ds_read_b64_tr_b16 v[238:239], v181 offset:0x3c00
	s_waitcnt lgkmcnt(6)
	v_mfma_f32_32x32x16_bf16 v[32:47], v[148:151], v[224:227], v[32:47]
	ds_read_b64_tr_b16 v[224:225], v181 offset:0x600
	ds_read_b64_tr_b16 v[226:227], v181 offset:0xe00
	s_waitcnt lgkmcnt(6)
	v_mfma_f32_32x32x16_bf16 v[32:47], v[152:155], v[228:231], v[32:47]
	ds_read_b64_tr_b16 v[228:229], v181 offset:0x1600
	ds_read_b64_tr_b16 v[230:231], v181 offset:0x1e00
	s_waitcnt lgkmcnt(6)
	v_mfma_f32_32x32x16_bf16 v[32:47], v[216:219], v[232:235], v[32:47]
	ds_read_b64_tr_b16 v[232:233], v181 offset:0x2600
	ds_read_b64_tr_b16 v[234:235], v181 offset:0x2e00
	s_waitcnt lgkmcnt(6)
	v_mfma_f32_32x32x16_bf16 v[32:47], v[220:223], v[236:239], v[32:47]
	ds_read_b64_tr_b16 v[236:237], v181 offset:0x3600
	ds_read_b64_tr_b16 v[238:239], v181 offset:0x3e00
	s_waitcnt lgkmcnt(6)
	v_mfma_f32_32x32x16_bf16 v[16:31], v[148:151], v[224:227], v[16:31]
	v_max_f32_e32 v148, v81, v81
	v_max_f32_e32 v149, v80, v80
	v_max_f32_e32 v148, v149, v148
	v_max3_f32 v148, v148, v82, v83
	v_max3_f32 v148, v148, v84, v85
	v_max3_f32 v148, v148, v86, v87
	v_max3_f32 v148, v148, v88, v89
	v_max3_f32 v148, v148, v90, v91
	v_max3_f32 v148, v148, v92, v93
	s_waitcnt lgkmcnt(4)
	v_mfma_f32_32x32x16_bf16 v[16:31], v[152:155], v[228:231], v[16:31]
	v_max3_f32 v148, v148, v94, v95
	v_max3_f32 v148, v148, v64, v65
	v_max3_f32 v148, v148, v66, v67
	v_max3_f32 v148, v148, v68, v69
	v_max3_f32 v148, v148, v70, v71
	v_max3_f32 v148, v148, v72, v73
	v_max3_f32 v148, v148, v74, v75
	v_max3_f32 v148, v148, v76, v77
	s_waitcnt lgkmcnt(2)
	v_mfma_f32_32x32x16_bf16 v[16:31], v[216:219], v[232:235], v[16:31]
	v_max3_f32 v148, v148, v78, v79
	v_mov_b32_e32 v149, v148
	s_nop 1
	v_permlane32_swap_b32_e32 v148, v149
	v_max_f32_e32 v149, v149, v149
	v_max_f32_e32 v148, v148, v148
	v_max_f32_e32 v148, v148, v149
	v_sub_f32_e32 v149, v148, v209
	v_cmp_ge_f32_e32 vcc, s90, v149
	v_max_f32_e32 v149, v209, v209
	v_max_f32_e32 v148, v149, v148
	s_waitcnt lgkmcnt(0)
	v_mfma_f32_32x32x16_bf16 v[16:31], v[220:223], v[236:239], v[16:31]
	v_sub_f32_e32 v149, v209, v148
	v_mul_f32_e32 v149, 0x3dd53b94, v149
	v_exp_f32_e32 v149, v149
	s_cmp_eq_u64 vcc, exec
	s_cselect_b64 s[6:7], -1, 0
	s_barrier
	s_waitcnt vmcnt(0)
	v_cndmask_b32_e64 v152, v149, 1.0, s[6:7]
	ds_write_b128 v185, v[128:131]
	ds_write_b128 v186, v[140:143]
	v_cmp_gt_f32_e32 vcc, 1.0, v152
	s_cbranch_vccz .LBB0_565
	s_and_saveexec_b64 s[0:1], s[4:5]
	ds_write_b32 v178, v152 offset:128
	s_or_b64 exec, exec, s[0:1]
	s_waitcnt lgkmcnt(0)
	v_add_u32_e32 v140, v157, v160
	ds_read_b128 v[128:131], v140 offset:224
	ds_read_b128 v[132:135], v140 offset:192
	ds_read_b128 v[136:139], v140 offset:160
	ds_read_b128 v[140:143], v140 offset:128
	s_waitcnt lgkmcnt(3)
	v_pk_mul_f32 v[12:13], v[12:13], v[128:129]
	s_waitcnt lgkmcnt(2)
	v_pk_mul_f32 v[8:9], v[8:9], v[132:133]
	s_waitcnt lgkmcnt(1)
	v_pk_mul_f32 v[4:5], v[4:5], v[136:137]
	v_pk_mul_f32 v[14:15], v[14:15], v[130:131]
	v_pk_mul_f32 v[10:11], v[10:11], v[134:135]
	v_pk_mul_f32 v[6:7], v[6:7], v[138:139]
	s_waitcnt lgkmcnt(0)
	v_pk_mul_f32 v[2:3], v[2:3], v[142:143]
	v_pk_mul_f32 v[0:1], v[0:1], v[140:141]
	v_pk_mul_f32 v[60:61], v[60:61], v[128:129]
	v_pk_mul_f32 v[56:57], v[56:57], v[132:133]
	v_pk_mul_f32 v[52:53], v[52:53], v[136:137]
	v_pk_mul_f32 v[62:63], v[62:63], v[130:131]
	v_pk_mul_f32 v[58:59], v[58:59], v[134:135]
	v_pk_mul_f32 v[54:55], v[54:55], v[138:139]
	v_pk_mul_f32 v[50:51], v[50:51], v[142:143]
	v_pk_mul_f32 v[48:49], v[48:49], v[140:141]
	v_pk_mul_f32 v[44:45], v[44:45], v[128:129]
	v_pk_mul_f32 v[40:41], v[40:41], v[132:133]
	v_pk_mul_f32 v[36:37], v[36:37], v[136:137]
	v_pk_mul_f32 v[46:47], v[46:47], v[130:131]
	v_pk_mul_f32 v[42:43], v[42:43], v[134:135]
	v_pk_mul_f32 v[38:39], v[38:39], v[138:139]
	v_pk_mul_f32 v[34:35], v[34:35], v[142:143]
	v_pk_mul_f32 v[32:33], v[32:33], v[140:141]
	v_pk_mul_f32 v[28:29], v[28:29], v[128:129]
	v_pk_mul_f32 v[24:25], v[24:25], v[132:133]
	v_pk_mul_f32 v[20:21], v[20:21], v[136:137]
	v_pk_mul_f32 v[30:31], v[30:31], v[130:131]
	v_pk_mul_f32 v[26:27], v[26:27], v[134:135]
	v_pk_mul_f32 v[22:23], v[22:23], v[138:139]
	v_pk_mul_f32 v[18:19], v[18:19], v[142:143]
	v_pk_mul_f32 v[16:17], v[16:17], v[140:141]
.LBB0_565:
	v_cndmask_b32_e64 v153, v148, v209, s[6:7]
	v_mul_f32_e32 v144, 0xbdd53b94, v153
	v_fmamk_f32 v141, v80, 0x3dd53b94, v144
	v_fmamk_f32 v143, v81, 0x3dd53b94, v144
	v_fmamk_f32 v139, v82, 0x3dd53b94, v144
	v_fmamk_f32 v142, v83, 0x3dd53b94, v144
	v_fmamk_f32 v138, v84, 0x3dd53b94, v144
	v_fmamk_f32 v140, v85, 0x3dd53b94, v144
	v_fmamk_f32 v136, v86, 0x3dd53b94, v144
	v_fmamk_f32 v137, v87, 0x3dd53b94, v144
	v_fmamk_f32 v133, v88, 0x3dd53b94, v144
	v_fmamk_f32 v135, v89, 0x3dd53b94, v144
	v_fmamk_f32 v132, v90, 0x3dd53b94, v144
	v_fmamk_f32 v134, v91, 0x3dd53b94, v144
	v_fmamk_f32 v129, v92, 0x3dd53b94, v144
	v_fmamk_f32 v131, v93, 0x3dd53b94, v144
	v_fmamk_f32 v128, v94, 0x3dd53b94, v144
	v_fmamk_f32 v130, v95, 0x3dd53b94, v144
	v_fmamk_f32 v218, v68, 0x3dd53b94, v144
	v_fmamk_f32 v148, v71, 0x3dd53b94, v144
	v_fmamk_f32 v149, v72, 0x3dd53b94, v144
	v_fmamk_f32 v219, v77, 0x3dd53b94, v144
	v_fmamk_f32 v155, v64, 0x3dd53b94, v144
	v_fmamk_f32 v209, v65, 0x3dd53b94, v144
	v_fmamk_f32 v216, v66, 0x3dd53b94, v144
	v_fmamk_f32 v217, v67, 0x3dd53b94, v144
	v_fmamk_f32 v146, v69, 0x3dd53b94, v144
	v_fmamk_f32 v147, v70, 0x3dd53b94, v144
	v_fmamk_f32 v150, v73, 0x3dd53b94, v144
	v_fmamk_f32 v151, v74, 0x3dd53b94, v144
	v_fmamk_f32 v154, v75, 0x3dd53b94, v144
	v_fmamk_f32 v145, v76, 0x3dd53b94, v144
	v_fmamk_f32 v220, v78, 0x3dd53b94, v144
	v_fmac_f32_e32 v144, 0x3dd53b94, v79
	s_waitcnt lgkmcnt(0)
	s_barrier
	ds_read_b128 v[64:67], v189 offset:32768
	ds_read_b128 v[68:71], v189 offset:40960
	ds_read_b128 v[222:225], v190 offset:32768
	ds_read_b128 v[226:229], v190 offset:40960
	v_exp_f32_e32 v155, v155
	v_exp_f32_e32 v209, v209
	s_waitcnt lgkmcnt(3)
	v_mfma_f32_32x32x16_bf16 v[80:95], v[64:67], v[120:123], 0
	v_xor_b32_e32 v241, v243, v158
	s_add_u32 s100, s64, 0x34ec0000
	s_addc_u32 s101, s65, 0
	s_lshl_b32 m0, s33, 4
	s_add_i32 m0, m0, 0xc000
	s_nop 0
	global_load_lds_dwordx4 v241, s[100:101]
	s_add_u32 s100, s64, 0x34ee0000
	s_addc_u32 s101, s65, 0
	s_add_i32 m0, m0, 0x2000
	s_nop 0
	global_load_lds_dwordx4 v241, s[100:101]
	v_xor_b32_e32 v241, v242, v170
	s_add_u32 s100, s64, 0x1ea06000
	s_addc_u32 s101, s65, 0
	s_add_i32 m0, m0, 0x4000
	s_nop 0
	global_load_lds_dwordx4 v241, s[100:101]
	v_exp_f32_e32 v216, v216
	v_exp_f32_e32 v217, v217
	s_waitcnt lgkmcnt(2)
	v_mfma_f32_32x32x16_bf16 v[64:79], v[68:71], v[120:123], 0
	v_exp_f32_e32 v141, v141
	v_exp_f32_e32 v143, v143
	v_add_f32_e32 v240, 0, v141
	v_exp_f32_e32 v139, v139
	v_add_f32_e32 v240, v143, v240
	s_waitcnt lgkmcnt(0)
	v_mfma_f32_32x32x16_bf16 v[64:79], v[226:229], v[124:127], v[64:79]
	v_exp_f32_e32 v142, v142
	v_add_f32_e32 v240, v139, v240
	v_exp_f32_e32 v138, v138
	v_add_f32_e32 v240, v142, v240
	v_mfma_f32_32x32x16_bf16 v[80:95], v[222:225], v[124:127], v[80:95]
	v_exp_f32_e32 v146, v146
	v_exp_f32_e32 v140, v140
	v_add_f32_e32 v240, v138, v240
	ds_read_b128 v[222:225], v191 offset:32768
	ds_read_b128 v[226:229], v191 offset:40960
	s_waitcnt lgkmcnt(0)
	v_mfma_f32_32x32x16_bf16 v[64:79], v[226:229], v[116:119], v[64:79]
	v_exp_f32_e32 v136, v136
	v_add_f32_e32 v240, v140, v240
	v_exp_f32_e32 v147, v147
	v_mfma_f32_32x32x16_bf16 v[80:95], v[222:225], v[116:119], v[80:95]
	v_exp_f32_e32 v137, v137
	v_add_f32_e32 v240, v136, v240
	v_exp_f32_e32 v133, v133
	v_add_f32_e32 v240, v137, v240
	ds_read_b128 v[222:225], v192 offset:32768
	ds_read_b128 v[226:229], v192 offset:40960
	s_waitcnt lgkmcnt(0)
	v_mfma_f32_32x32x16_bf16 v[64:79], v[226:229], v[112:115], v[64:79]
	v_exp_f32_e32 v154, v154
	v_exp_f32_e32 v135, v135
	v_add_f32_e32 v240, v133, v240
	v_mfma_f32_32x32x16_bf16 v[80:95], v[222:225], v[112:115], v[80:95]
	v_exp_f32_e32 v132, v132
	v_add_f32_e32 v240, v135, v240
	v_exp_f32_e32 v145, v145
	ds_read_b128 v[222:225], v193 offset:32768
	ds_read_b128 v[226:229], v193 offset:40960
	s_waitcnt lgkmcnt(0)
	v_mfma_f32_32x32x16_bf16 v[64:79], v[226:229], v[108:111], v[64:79]
	v_exp_f32_e32 v134, v134
	v_add_f32_e32 v240, v132, v240
	v_exp_f32_e32 v129, v129
	v_add_f32_e32 v240, v134, v240
	v_mfma_f32_32x32x16_bf16 v[80:95], v[222:225], v[108:111], v[80:95]
	v_exp_f32_e32 v144, v144
	v_exp_f32_e32 v131, v131
	v_add_f32_e32 v240, v129, v240
	ds_read_b128 v[222:225], v194 offset:32768
	ds_read_b128 v[226:229], v194 offset:40960
	s_waitcnt lgkmcnt(0)
	v_mfma_f32_32x32x16_bf16 v[64:79], v[226:229], v[104:107], v[64:79]
	v_exp_f32_e32 v128, v128
	v_add_f32_e32 v240, v131, v240
	v_exp_f32_e32 v218, v218
	v_mfma_f32_32x32x16_bf16 v[80:95], v[222:225], v[104:107], v[80:95]
	v_exp_f32_e32 v130, v130
	v_add_f32_e32 v240, v128, v240
	v_add_f32_e32 v240, v130, v240
	ds_read_b128 v[222:225], v195 offset:32768
	ds_read_b128 v[226:229], v195 offset:40960
	s_waitcnt lgkmcnt(0)
	v_mfma_f32_32x32x16_bf16 v[64:79], v[226:229], v[100:103], v[64:79]
	v_exp_f32_e32 v148, v148
	v_add_f32_e32 v240, v155, v240
	v_mfma_f32_32x32x16_bf16 v[80:95], v[222:225], v[100:103], v[80:95]
	v_add_f32_e32 v240, v209, v240
	v_exp_f32_e32 v149, v149
	ds_read_b128 v[222:225], v196 offset:32768
	ds_read_b128 v[226:229], v196 offset:40960
	s_waitcnt lgkmcnt(0)
	v_mfma_f32_32x32x16_bf16 v[64:79], v[226:229], v[96:99], v[64:79]
	v_add_f32_e32 v240, v216, v240
	v_add_f32_e32 v240, v217, v240
	v_mfma_f32_32x32x16_bf16 v[80:95], v[222:225], v[96:99], v[80:95]
	v_exp_f32_e32 v150, v150
	v_add_f32_e32 v240, v218, v240
	ds_read_b128 v[222:225], v199
	ds_read_b128 v[226:229], v199 offset:4096
	ds_read_b128 v[230:233], v197
	s_waitcnt lgkmcnt(0)
	v_mfma_f32_32x32x16_bf16 v[64:79], v[226:229], v[230:233], v[64:79]
	v_add_f32_e32 v240, v146, v240
	v_exp_f32_e32 v151, v151
	v_mfma_f32_32x32x16_bf16 v[80:95], v[222:225], v[230:233], v[80:95]
	v_add_f32_e32 v240, v147, v240
	v_add_f32_e32 v240, v148, v240
	ds_read_b128 v[222:225], v201
	ds_read_b128 v[226:229], v201 offset:4096
	ds_read_b128 v[230:233], v184
	s_waitcnt lgkmcnt(0)
	v_mfma_f32_32x32x16_bf16 v[64:79], v[226:229], v[230:233], v[64:79]
	v_exp_f32_e32 v219, v219
	v_add_f32_e32 v240, v149, v240
	v_mfma_f32_32x32x16_bf16 v[80:95], v[222:225], v[230:233], v[80:95]
	v_add_f32_e32 v240, v150, v240
	v_exp_f32_e32 v220, v220
	ds_read_b128 v[222:225], v203
	ds_read_b128 v[226:229], v203 offset:4096
	ds_read_b128 v[230:233], v183
	s_waitcnt lgkmcnt(0)
	v_mfma_f32_32x32x16_bf16 v[64:79], v[226:229], v[230:233], v[64:79]
	v_add_f32_e32 v240, v151, v240
	v_add_f32_e32 v240, v154, v240
	v_mfma_f32_32x32x16_bf16 v[80:95], v[222:225], v[230:233], v[80:95]
	v_add_f32_e32 v240, v145, v240
	v_add_f32_e32 v240, v219, v240
	ds_read_b128 v[222:225], v205
	ds_read_b128 v[226:229], v205 offset:4096
	ds_read_b128 v[230:233], v182
	s_waitcnt lgkmcnt(0)
	v_mfma_f32_32x32x16_bf16 v[64:79], v[226:229], v[230:233], v[64:79]
	v_add_f32_e32 v240, v220, v240
	v_add_f32_e32 v240, v144, v240
	v_mfma_f32_32x32x16_bf16 v[80:95], v[222:225], v[230:233], v[80:95]
	v_cvt_pk_bf16_f32 v226, v218, v146
	v_cvt_pk_bf16_f32 v227, v147, v148
	v_cvt_pk_bf16_f32 v228, v149, v150
	v_cvt_pk_bf16_f32 v229, v151, v154
	v_cvt_pk_bf16_f32 v230, v145, v219
	v_cvt_pk_bf16_f32 v231, v220, v144
	v_mov_b32_e32 v218, v240
	v_mov_b32_e32 v219, v240
	v_cvt_pk_bf16_f32 v148, v141, v143
	v_cvt_pk_bf16_f32 v149, v139, v142
	v_cvt_pk_bf16_f32 v150, v138, v140
	v_cvt_pk_bf16_f32 v151, v136, v137
	v_permlane32_swap_b32_e32 v218, v219
	v_permlane32_swap_b32_e32 v148, v150
	v_permlane32_swap_b32_e32 v149, v151
	v_cvt_pk_bf16_f32 v220, v133, v135
	v_cvt_pk_bf16_f32 v221, v132, v134
	v_cvt_pk_bf16_f32 v222, v129, v131
	v_cvt_pk_bf16_f32 v223, v128, v130
	v_cvt_pk_bf16_f32 v224, v155, v209
	v_cvt_pk_bf16_f32 v225, v216, v217
	s_nop 0
	v_permlane32_swap_b32_e32 v220, v222
	v_permlane32_swap_b32_e32 v221, v223
	v_permlane32_swap_b32_e32 v224, v226
	v_permlane32_swap_b32_e32 v225, v227
	v_permlane32_swap_b32_e32 v228, v230
	v_permlane32_swap_b32_e32 v229, v231
	s_mov_b32 s0, 0x34ec0000
	v_add_co_u32_e32 v132, vcc, s0, v172
	s_mov_b32 s0, 0x34ee0000
	s_nop 0
	v_addc_co_u32_e32 v133, vcc, 0, v173, vcc
	v_add_co_u32_e32 v136, vcc, s0, v172
	s_mov_b32 s0, 0x1ea06000
	s_nop 0
	v_addc_co_u32_e32 v137, vcc, 0, v173, vcc
	global_load_dwordx4 v[128:131], v[132:133], off offset:256
	s_nop 0
	s_nop 0
	global_load_dwordx4 v[140:143], v[136:137], off offset:256
	s_nop 0
	ds_read_b64_tr_b16 v[172:173], v180 offset:0
	ds_read_b64_tr_b16 v[174:175], v180 offset:0x800
	ds_read_b64_tr_b16 v[232:233], v180 offset:0x1000
	ds_read_b64_tr_b16 v[234:235], v180 offset:0x1800
	ds_read_b64_tr_b16 v[236:237], v180 offset:0x2000
	ds_read_b64_tr_b16 v[238:239], v180 offset:0x2800
	ds_read_b64_tr_b16 v[248:249], v180 offset:0x3000
	ds_read_b64_tr_b16 v[250:251], v180 offset:0x3800
	s_nop 0
	s_waitcnt lgkmcnt(6)
	v_mfma_f32_32x32x16_bf16 v[0:15], v[148:151], v[172:175], v[0:15]
	ds_read_b64_tr_b16 v[172:173], v180 offset:0x200
	ds_read_b64_tr_b16 v[174:175], v180 offset:0xa00
	s_waitcnt lgkmcnt(6)
	v_mfma_f32_32x32x16_bf16 v[0:15], v[220:223], v[232:235], v[0:15]
	ds_read_b64_tr_b16 v[232:233], v180 offset:0x1200
	ds_read_b64_tr_b16 v[234:235], v180 offset:0x1a00
	s_waitcnt lgkmcnt(6)
	v_mfma_f32_32x32x16_bf16 v[0:15], v[224:227], v[236:239], v[0:15]
	ds_read_b64_tr_b16 v[236:237], v180 offset:0x2200
	ds_read_b64_tr_b16 v[238:239], v180 offset:0x2a00
	s_waitcnt lgkmcnt(6)
	v_mfma_f32_32x32x16_bf16 v[0:15], v[228:231], v[248:251], v[0:15]
	ds_read_b64_tr_b16 v[248:249], v180 offset:0x3200
	ds_read_b64_tr_b16 v[250:251], v180 offset:0x3a00
	s_waitcnt lgkmcnt(6)
	v_mfma_f32_32x32x16_bf16 v[48:63], v[148:151], v[172:175], v[48:63]
	ds_read_b64_tr_b16 v[172:173], v180 offset:0x400
	ds_read_b64_tr_b16 v[174:175], v180 offset:0xc00
	s_waitcnt lgkmcnt(6)
	v_mfma_f32_32x32x16_bf16 v[48:63], v[220:223], v[232:235], v[48:63]
	ds_read_b64_tr_b16 v[232:233], v180 offset:0x1400
	ds_read_b64_tr_b16 v[234:235], v180 offset:0x1c00
	s_waitcnt lgkmcnt(6)
	v_mfma_f32_32x32x16_bf16 v[48:63], v[224:227], v[236:239], v[48:63]
	ds_read_b64_tr_b16 v[236:237], v180 offset:0x2400
	ds_read_b64_tr_b16 v[238:239], v180 offset:0x2c00
	s_waitcnt lgkmcnt(6)
	v_mfma_f32_32x32x16_bf16 v[48:63], v[228:231], v[248:251], v[48:63]
	ds_read_b64_tr_b16 v[248:249], v180 offset:0x3400
	ds_read_b64_tr_b16 v[250:251], v180 offset:0x3c00
	s_waitcnt lgkmcnt(6)
	v_mfma_f32_32x32x16_bf16 v[32:47], v[148:151], v[172:175], v[32:47]
	ds_read_b64_tr_b16 v[172:173], v180 offset:0x600
	ds_read_b64_tr_b16 v[174:175], v180 offset:0xe00
	s_waitcnt lgkmcnt(6)
	v_mfma_f32_32x32x16_bf16 v[32:47], v[220:223], v[232:235], v[32:47]
	ds_read_b64_tr_b16 v[232:233], v180 offset:0x1600
	ds_read_b64_tr_b16 v[234:235], v180 offset:0x1e00
	s_waitcnt lgkmcnt(6)
	v_mfma_f32_32x32x16_bf16 v[32:47], v[224:227], v[236:239], v[32:47]
	ds_read_b64_tr_b16 v[236:237], v180 offset:0x2600
	ds_read_b64_tr_b16 v[238:239], v180 offset:0x2e00
	s_waitcnt lgkmcnt(6)
	v_mfma_f32_32x32x16_bf16 v[32:47], v[228:231], v[248:251], v[32:47]
	ds_read_b64_tr_b16 v[248:249], v180 offset:0x3600
	ds_read_b64_tr_b16 v[250:251], v180 offset:0x3e00
	s_waitcnt lgkmcnt(6)
	v_mfma_f32_32x32x16_bf16 v[16:31], v[148:151], v[172:175], v[16:31]
	v_max_f32_e32 v148, v81, v81
	v_max_f32_e32 v149, v80, v80
	v_max_f32_e32 v148, v149, v148
	v_max3_f32 v148, v148, v82, v83
	v_max3_f32 v148, v148, v84, v85
	v_max3_f32 v148, v148, v86, v87
	v_max3_f32 v148, v148, v88, v89
	v_max3_f32 v148, v148, v90, v91
	v_max3_f32 v148, v148, v92, v93
	s_waitcnt lgkmcnt(4)
	v_mfma_f32_32x32x16_bf16 v[16:31], v[220:223], v[232:235], v[16:31]
	v_max3_f32 v148, v148, v94, v95
	v_max3_f32 v148, v148, v64, v65
	v_max3_f32 v148, v148, v66, v67
	v_max3_f32 v148, v148, v68, v69
	v_max3_f32 v148, v148, v70, v71
	v_max3_f32 v148, v148, v72, v73
	v_max3_f32 v148, v148, v74, v75
	v_max3_f32 v148, v148, v76, v77
	s_waitcnt lgkmcnt(2)
	v_mfma_f32_32x32x16_bf16 v[16:31], v[224:227], v[236:239], v[16:31]
	v_max3_f32 v148, v148, v78, v79
	v_mov_b32_e32 v149, v148
	s_nop 1
	v_permlane32_swap_b32_e32 v148, v149
	v_max_f32_e32 v149, v149, v149
	v_max_f32_e32 v148, v148, v148
	v_max_f32_e32 v148, v148, v149
	v_sub_f32_e32 v149, v148, v153
	v_cmp_ge_f32_e32 vcc, s90, v149
	v_max_f32_e32 v149, v153, v153
	v_max_f32_e32 v149, v149, v148
	s_waitcnt lgkmcnt(0)
	v_mfma_f32_32x32x16_bf16 v[16:31], v[228:231], v[248:251], v[16:31]
	v_sub_f32_e32 v148, v153, v149
	v_mul_f32_e32 v148, 0x3dd53b94, v148
	v_exp_f32_e32 v148, v148
	s_cmp_eq_u64 vcc, exec
	s_cselect_b64 s[6:7], -1, 0
	s_barrier
	s_waitcnt vmcnt(0)
	v_cndmask_b32_e64 v148, v148, 1.0, s[6:7]
	v_cmp_gt_f32_e32 vcc, 1.0, v148
	ds_write_b128 v185, v[128:131] offset:16384
	ds_write_b128 v186, v[140:143] offset:16384
	s_cbranch_vccz .LBB0_569
	s_and_saveexec_b64 s[0:1], s[4:5]
	ds_write_b32 v178, v148 offset:128
	s_or_b64 exec, exec, s[0:1]
	s_waitcnt lgkmcnt(0)
	v_add_u32_e32 v140, v157, v160
	ds_read_b128 v[128:131], v140 offset:224
	ds_read_b128 v[132:135], v140 offset:192
	ds_read_b128 v[136:139], v140 offset:160
	ds_read_b128 v[140:143], v140 offset:128
	s_waitcnt lgkmcnt(3)
	v_pk_mul_f32 v[12:13], v[12:13], v[128:129]
	s_waitcnt lgkmcnt(2)
	v_pk_mul_f32 v[8:9], v[8:9], v[132:133]
	s_waitcnt lgkmcnt(1)
	v_pk_mul_f32 v[4:5], v[4:5], v[136:137]
	v_pk_mul_f32 v[14:15], v[14:15], v[130:131]
	v_pk_mul_f32 v[10:11], v[10:11], v[134:135]
	v_pk_mul_f32 v[6:7], v[6:7], v[138:139]
	s_waitcnt lgkmcnt(0)
	v_pk_mul_f32 v[2:3], v[2:3], v[142:143]
	v_pk_mul_f32 v[0:1], v[0:1], v[140:141]
	v_pk_mul_f32 v[60:61], v[60:61], v[128:129]
	v_pk_mul_f32 v[56:57], v[56:57], v[132:133]
	v_pk_mul_f32 v[52:53], v[52:53], v[136:137]
	v_pk_mul_f32 v[62:63], v[62:63], v[130:131]
	v_pk_mul_f32 v[58:59], v[58:59], v[134:135]
	v_pk_mul_f32 v[54:55], v[54:55], v[138:139]
	v_pk_mul_f32 v[50:51], v[50:51], v[142:143]
	v_pk_mul_f32 v[48:49], v[48:49], v[140:141]
	v_pk_mul_f32 v[44:45], v[44:45], v[128:129]
	v_pk_mul_f32 v[40:41], v[40:41], v[132:133]
	v_pk_mul_f32 v[36:37], v[36:37], v[136:137]
	v_pk_mul_f32 v[46:47], v[46:47], v[130:131]
	v_pk_mul_f32 v[42:43], v[42:43], v[134:135]
	v_pk_mul_f32 v[38:39], v[38:39], v[138:139]
	v_pk_mul_f32 v[34:35], v[34:35], v[142:143]
	v_pk_mul_f32 v[32:33], v[32:33], v[140:141]
	v_pk_mul_f32 v[28:29], v[28:29], v[128:129]
	v_pk_mul_f32 v[24:25], v[24:25], v[132:133]
	v_pk_mul_f32 v[20:21], v[20:21], v[136:137]
	v_pk_mul_f32 v[30:31], v[30:31], v[130:131]
	v_pk_mul_f32 v[26:27], v[26:27], v[134:135]
	v_pk_mul_f32 v[22:23], v[22:23], v[138:139]
	v_pk_mul_f32 v[18:19], v[18:19], v[142:143]
	v_pk_mul_f32 v[16:17], v[16:17], v[140:141]
